# phase_init: the 4 float4 row loads issued together with one wait (was load/wait x4 per row)
# baseline (speedup 1.0000x reference)
; __device__ __forceinline__ bfr f2bf(float f) { return (bfr)(pack2(f, f) & 0xffffu); }
; __device__ __forceinline__ float bf2f(bfr b) { return __uint_as_float(((unsigned)b) << 16); }
; __device__ void phase_init(const KP& p) {
;     ...
;     float ss = 0.f;
; #pragma unroll
;     for (int i = 0; i < 4; ++i) {
;       int c = 4 * (lane + 64 * i);
;       float4 v = src ? *(const float4*)(src + c) : make_float4(0.f, 0.f, 0.f, 0.f);
;       bfr b0 = f2bf(v.x), b1 = f2bf(v.y), b2 = f2bf(v.z), b3 = f2bf(v.w);
;       float r0 = bf2f(b0), r1 = bf2f(b1), r2 = bf2f(b2), r3 = bf2f(b3);
;       ss += r0 * r0 + r1 * r1 + r2 * r2 + r3 * r3;
;       uint2 o; o.x = (unsigned)b0 | ((unsigned)b1 << 16); o.y = (unsigned)b2 | ((unsigned)b3 << 16);
;       *(uint2*)(hb + (size_t)row * DM + c) = o;
;     }
.LBB0_209:
	s_or_b64 exec, exec, s[40:41]
	s_waitcnt lgkmcnt(0)
	v_cmp_ne_u64_e64 s[0:1], 0, v[8:9]
	v_mov_b32_e32 v12, 0
	v_mov_b32_e32 v14, 0
	v_mov_b32_e32 v5, 0
	v_mov_b32_e32 v23, 0
	v_mov_b32_e32 v24, 0
	s_and_saveexec_b64 s[40:41], s[0:1]
	s_cbranch_execz .LBB0_211
	v_lshlrev_b32_e32 v0, 2, v4
	v_lshl_add_u64 v[10:11], v[8:9], 0, v[0:1]
	global_load_dwordx4 v[24:27], v[10:11], off
	global_load_dwordx4 v[40:43], v[10:11], off offset:1024
	global_load_dwordx4 v[44:47], v[10:11], off offset:2048
	global_load_dwordx4 v[48:51], v[10:11], off offset:3072
	s_waitcnt vmcnt(0)
	v_cvt_pk_bf16_f32 v0, v24, v26
	v_cvt_pk_bf16_f32 v3, v25, v27
	v_and_b32_e32 v23, 0xffff, v0
	v_lshrrev_b32_e32 v24, 16, v0
	v_and_b32_e32 v5, 0xffff0000, v3
	v_lshlrev_b32_e32 v14, 16, v3
.LBB0_211:
	s_or_b64 exec, exec, s[40:41]
	v_ashrrev_i32_e32 v3, 31, v2
	v_lshlrev_b64 v[10:11], 11, v[2:3]
	v_or_b32_e32 v27, v5, v24
	v_or_b32_e32 v26, v14, v23
	v_lshl_add_u64 v[10:11], v[6:7], 0, v[10:11]
	global_store_dwordx2 v[10:11], v[26:27], off
	s_waitcnt lgkmcnt(0)
	v_mov_b32_e32 v13, 0
	v_mov_b32_e32 v26, 0
	v_mov_b32_e32 v27, 0
	s_and_saveexec_b64 s[40:41], s[0:1]
	s_cbranch_execz .LBB0_213
	v_mov_b32_e32 v26, v40
	v_mov_b32_e32 v27, v41
	v_mov_b32_e32 v28, v42
	v_mov_b32_e32 v29, v43
	v_cvt_pk_bf16_f32 v0, v26, v28
	v_cvt_pk_bf16_f32 v12, v27, v29
	v_and_b32_e32 v26, 0xffff, v0
	v_lshrrev_b32_e32 v27, 16, v0
	v_and_b32_e32 v13, 0xffff0000, v12
	v_lshlrev_b32_e32 v12, 16, v12
.LBB0_213:
	s_or_b64 exec, exec, s[40:41]
	v_or_b32_e32 v29, v13, v27
	v_or_b32_e32 v28, v12, v26
	global_store_dwordx2 v[10:11], v[28:29], off offset:512
	v_mov_b32_e32 v25, 0
	v_mov_b32_e32 v16, 0
	v_mov_b32_e32 v15, 0
	v_mov_b32_e32 v28, 0
	v_mov_b32_e32 v29, 0
	s_and_saveexec_b64 s[40:41], s[0:1]
	s_cbranch_execz .LBB0_215
	v_mov_b32_e32 v28, v44
	v_mov_b32_e32 v29, v45
	v_mov_b32_e32 v30, v46
	v_mov_b32_e32 v31, v47
	v_cvt_pk_bf16_f32 v0, v28, v30
	v_cvt_pk_bf16_f32 v16, v29, v31
	v_and_b32_e32 v28, 0xffff, v0
	v_lshrrev_b32_e32 v29, 16, v0
	v_and_b32_e32 v15, 0xffff0000, v16
	v_lshlrev_b32_e32 v16, 16, v16
.LBB0_215:
	s_or_b64 exec, exec, s[40:41]
	v_or_b32_e32 v31, v15, v29
	v_or_b32_e32 v30, v16, v28
	global_store_dwordx2 v[10:11], v[30:31], off offset:1024
	v_mov_b32_e32 v30, 0
	v_mov_b32_e32 v0, 0
	v_mov_b32_e32 v31, 0
	s_and_saveexec_b64 s[40:41], s[0:1]
	s_cbranch_execz .LBB0_217
	v_mov_b32_e32 v30, v48
	v_mov_b32_e32 v31, v49
	v_mov_b32_e32 v32, v50
	v_mov_b32_e32 v33, v51
	v_cvt_pk_bf16_f32 v8, v30, v32
	v_cvt_pk_bf16_f32 v9, v31, v33
	v_and_b32_e32 v0, 0xffff, v8
	v_lshrrev_b32_e32 v31, 16, v8
	v_and_b32_e32 v30, 0xffff0000, v9
	v_lshlrev_b32_e32 v25, 16, v9
